# noinv1: stack4 + attention-post row loads made device-coherent (sc1) and the whole-L2 invalidate behind every post-queue pop dropped
# speedup vs baseline: 1.0151x; 1.0151x over previous
.LBB0_617:
	v_add_u32_e32 v6, -12, v14
	v_add_u32_e32 v18, -8, v14
	v_add_u32_e32 v20, -4, v14
	v_ashrrev_i32_e32 v15, 31, v14
	v_ashrrev_i32_e32 v7, 31, v6
	v_ashrrev_i32_e32 v19, 31, v18
	v_ashrrev_i32_e32 v21, 31, v20
	v_lshlrev_b64 v[22:23], 10, v[14:15]
	v_lshlrev_b64 v[32:33], 10, v[6:7]
	v_lshlrev_b64 v[34:35], 10, v[18:19]
	v_lshlrev_b64 v[36:37], 10, v[20:21]
	v_lshlrev_b64 v[24:25], 11, v[14:15]
	v_or_b32_e32 v22, v22, v8
	v_or_b32_e32 v32, v32, v8
	v_or_b32_e32 v34, v34, v8
	v_or_b32_e32 v36, v36, v8
	v_lshlrev_b64 v[26:27], 11, v[6:7]
	v_lshlrev_b64 v[18:19], 11, v[18:19]
	v_lshlrev_b64 v[28:29], 11, v[20:21]
	v_lshl_add_u64 v[6:7], v[12:13], 0, v[24:25]
	v_lshl_add_u64 v[76:77], s[18:19], 0, v[22:23]
	v_lshl_add_u64 v[24:25], s[22:23], 0, v[22:23]
	v_lshl_add_u64 v[30:31], s[48:49], 0, v[22:23]
	v_lshl_add_u64 v[44:45], s[18:19], 0, v[32:33]
	v_lshl_add_u64 v[46:47], s[22:23], 0, v[32:33]
	v_lshl_add_u64 v[48:49], s[48:49], 0, v[32:33]
	v_lshl_add_u64 v[56:57], s[18:19], 0, v[34:35]
	v_lshl_add_u64 v[52:53], s[22:23], 0, v[34:35]
	v_lshl_add_u64 v[60:61], s[48:49], 0, v[34:35]
	v_lshl_add_u64 v[68:69], s[18:19], 0, v[36:37]
	v_lshl_add_u64 v[64:65], s[22:23], 0, v[36:37]
	v_lshl_add_u64 v[22:23], v[12:13], 0, v[26:27]
	v_lshl_add_u64 v[20:21], v[12:13], 0, v[18:19]
	v_lshl_add_u64 v[18:19], v[12:13], 0, v[28:29]
	global_load_dwordx4 v[24:27], v[24:25], off sc1
	v_lshl_add_u64 v[36:37], s[48:49], 0, v[36:37]
	global_load_dwordx4 v[28:31], v[30:31], off sc1
	s_nop 0
	global_load_dwordx4 v[32:35], v[46:47], off sc1
	s_nop 0
	global_load_dwordx4 v[44:47], v[44:45], off sc1
	s_nop 0
	global_load_dwordx4 v[48:51], v[48:49], off sc1
	s_nop 0
	global_load_dwordx4 v[52:55], v[52:53], off sc1
	s_nop 0
	global_load_dwordx4 v[56:59], v[56:57], off sc1
	s_nop 0
	global_load_dwordx4 v[60:63], v[60:61], off sc1
	s_nop 0
	global_load_dwordx4 v[64:67], v[64:65], off sc1
	s_nop 0
	global_load_dwordx4 v[68:71], v[68:69], off sc1
	s_nop 0
	global_load_dwordx4 v[72:75], v[36:37], off sc1
	s_nop 0
	global_load_dwordx4 v[76:79], v[76:77], off sc1
	s_add_i32 s41, s41, 8
	s_cmp_lt_i32 s41, 8
	v_add_u32_e32 v14, 0x80, v14
	s_waitcnt vmcnt(9)
	v_lshlrev_b32_e32 v88, 16, v32
	v_lshlrev_b32_e32 v89, 16, v33
	s_waitcnt vmcnt(8)
	v_lshlrev_b32_e32 v97, 16, v45
	v_lshlrev_b32_e32 v96, 16, v44
	v_and_b32_e32 v90, 0xffff0000, v32
	v_and_b32_e32 v91, 0xffff0000, v33
	v_lshlrev_b32_e32 v80, 16, v24
	v_lshlrev_b32_e32 v81, 16, v25
	v_lshlrev_b32_e32 v92, 16, v34
	v_and_b32_e32 v94, 0xffff0000, v34
	v_lshlrev_b32_e32 v93, 16, v35
	v_and_b32_e32 v95, 0xffff0000, v35
	v_and_b32_e32 v45, 0xffff0000, v45
	v_and_b32_e32 v44, 0xffff0000, v44
	v_lshlrev_b32_e32 v99, 16, v47
	v_lshlrev_b32_e32 v98, 16, v46
	s_waitcnt vmcnt(6)
	v_lshlrev_b32_e32 v104, 16, v54
	v_and_b32_e32 v54, 0xffff0000, v54
	v_lshlrev_b32_e32 v105, 16, v55
	v_and_b32_e32 v55, 0xffff0000, v55
	s_waitcnt vmcnt(5)
	v_lshlrev_b32_e32 v111, 16, v59
	v_lshlrev_b32_e32 v110, 16, v58
	v_and_b32_e32 v59, 0xffff0000, v59
	v_and_b32_e32 v58, 0xffff0000, v58
	s_waitcnt vmcnt(3)
	v_lshlrev_b32_e32 v114, 16, v64
	v_lshlrev_b32_e32 v115, 16, v65
	v_lshlrev_b32_e32 v116, 16, v66
	v_and_b32_e32 v66, 0xffff0000, v66
	v_lshlrev_b32_e32 v117, 16, v67
	v_and_b32_e32 v67, 0xffff0000, v67
	s_waitcnt vmcnt(2)
	v_lshlrev_b32_e32 v119, 16, v69
	v_lshlrev_b32_e32 v118, 16, v68
	s_waitcnt vmcnt(1)
	v_lshlrev_b32_e32 v33, 16, v73
	v_lshlrev_b32_e32 v32, 16, v72
	v_and_b32_e32 v35, 0xffff0000, v73
	v_and_b32_e32 v34, 0xffff0000, v72
	v_lshlrev_b32_e32 v73, 16, v71
	v_lshlrev_b32_e32 v72, 16, v70
	v_and_b32_e32 v71, 0xffff0000, v71
	v_and_b32_e32 v70, 0xffff0000, v70
	s_waitcnt vmcnt(0)
	v_lshlrev_b32_e32 v123, 16, v77
	v_lshlrev_b32_e32 v122, 16, v76
	v_pk_fma_f32 v[88:89], v[10:11], v[88:89], v[96:97] neg_lo:[1,0,0] neg_hi:[1,0,0]
	v_and_b32_e32 v82, 0xffff0000, v24
	v_and_b32_e32 v83, 0xffff0000, v25
	v_and_b32_e32 v47, 0xffff0000, v47
	v_and_b32_e32 v46, 0xffff0000, v46
	v_lshlrev_b32_e32 v102, 16, v52
	v_lshlrev_b32_e32 v103, 16, v53
	v_lshlrev_b32_e32 v107, 16, v57
	v_lshlrev_b32_e32 v106, 16, v56
	v_and_b32_e32 v64, 0xffff0000, v64
	v_and_b32_e32 v65, 0xffff0000, v65
	v_and_b32_e32 v69, 0xffff0000, v69
	v_and_b32_e32 v68, 0xffff0000, v68
	v_and_b32_e32 v77, 0xffff0000, v77
	v_and_b32_e32 v76, 0xffff0000, v76
	v_pk_fma_f32 v[44:45], v[10:11], v[90:91], v[44:45] neg_lo:[1,0,0] neg_hi:[1,0,0]
	v_pk_fma_f32 v[90:91], v[10:11], v[92:93], v[98:99] neg_lo:[1,0,0] neg_hi:[1,0,0]
	v_pk_fma_f32 v[54:55], v[10:11], v[54:55], v[58:59] neg_lo:[1,0,0] neg_hi:[1,0,0]
	v_pk_fma_f32 v[58:59], v[10:11], v[114:115], v[118:119] neg_lo:[1,0,0] neg_hi:[1,0,0]
	v_pk_fma_f32 v[66:67], v[10:11], v[66:67], v[70:71] neg_lo:[1,0,0] neg_hi:[1,0,0]
	v_pk_fma_f32 v[70:71], v[10:11], v[80:81], v[122:123] neg_lo:[1,0,0] neg_hi:[1,0,0]
	v_pk_mul_f32 v[80:81], v[88:89], v[88:89]
	v_lshlrev_b32_e32 v84, 16, v26
	v_lshlrev_b32_e32 v85, 16, v27
	v_and_b32_e32 v52, 0xffff0000, v52
	v_and_b32_e32 v53, 0xffff0000, v53
	v_and_b32_e32 v57, 0xffff0000, v57
	v_and_b32_e32 v56, 0xffff0000, v56
	v_lshlrev_b32_e32 v125, 16, v79
	v_lshlrev_b32_e32 v124, 16, v78
	v_pk_fma_f32 v[46:47], v[10:11], v[94:95], v[46:47] neg_lo:[1,0,0] neg_hi:[1,0,0]
	v_pk_fma_f32 v[92:93], v[10:11], v[102:103], v[106:107] neg_lo:[1,0,0] neg_hi:[1,0,0]
	v_pk_fma_f32 v[64:65], v[10:11], v[64:65], v[68:69] neg_lo:[1,0,0] neg_hi:[1,0,0]
	v_pk_fma_f32 v[68:69], v[10:11], v[116:117], v[72:73] neg_lo:[1,0,0] neg_hi:[1,0,0]
	v_pk_fma_f32 v[72:73], v[10:11], v[82:83], v[76:77] neg_lo:[1,0,0] neg_hi:[1,0,0]
	v_pk_mul_f32 v[82:83], v[90:91], v[90:91]
	v_pk_mul_f32 v[94:95], v[58:59], v[58:59]
	v_pk_fma_f32 v[80:81], v[44:45], v[44:45], v[80:81]
	v_and_b32_e32 v86, 0xffff0000, v26
	v_and_b32_e32 v87, 0xffff0000, v27
	v_and_b32_e32 v79, 0xffff0000, v79
	v_and_b32_e32 v78, 0xffff0000, v78
	v_pk_fma_f32 v[52:53], v[10:11], v[52:53], v[56:57] neg_lo:[1,0,0] neg_hi:[1,0,0]
	v_pk_fma_f32 v[56:57], v[10:11], v[104:105], v[110:111] neg_lo:[1,0,0] neg_hi:[1,0,0]
	v_pk_fma_f32 v[76:77], v[10:11], v[84:85], v[124:125] neg_lo:[1,0,0] neg_hi:[1,0,0]
	v_pk_mul_f32 v[84:85], v[92:93], v[92:93]
	v_pk_mul_f32 v[96:97], v[68:69], v[68:69]
	v_pk_fma_f32 v[82:83], v[46:47], v[46:47], v[82:83]
	v_pk_fma_f32 v[94:95], v[64:65], v[64:65], v[94:95]
	v_add_f32_e32 v15, v80, v81
	v_pk_fma_f32 v[78:79], v[10:11], v[86:87], v[78:79] neg_lo:[1,0,0] neg_hi:[1,0,0]
	v_pk_mul_f32 v[86:87], v[56:57], v[56:57]
	v_pk_fma_f32 v[84:85], v[52:53], v[52:53], v[84:85]
	v_pk_fma_f32 v[96:97], v[66:67], v[66:67], v[96:97]
	v_add_f32_e32 v80, v94, v95
	v_add_f32_e32 v15, v82, v15
	v_pk_mul_f32 v[98:99], v[70:71], v[70:71]
	v_pk_fma_f32 v[86:87], v[54:55], v[54:55], v[86:87]
	v_add_f32_e32 v43, v84, v85
	v_add_f32_e32 v80, v96, v80
	v_add_f32_e32 v15, v83, v15
	v_pk_mul_f32 v[102:103], v[76:77], v[76:77]
	v_pk_fma_f32 v[98:99], v[72:73], v[72:73], v[98:99]
	v_add_f32_e32 v43, v86, v43
	v_add_f32_e32 v80, v97, v80
	v_add_f32_dpp v15, v15, v15 quad_perm:[1,0,3,2] row_mask:0xf bank_mask:0xf bound_ctrl:1
	v_pk_fma_f32 v[102:103], v[78:79], v[78:79], v[102:103]
	v_add_f32_e32 v81, v98, v99
	v_add_f32_e32 v43, v87, v43
	v_add_f32_dpp v80, v80, v80 quad_perm:[1,0,3,2] row_mask:0xf bank_mask:0xf bound_ctrl:1
	v_add_f32_dpp v15, v15, v15 quad_perm:[2,3,0,1] row_mask:0xf bank_mask:0xf bound_ctrl:1
	v_add_f32_e32 v81, v102, v81
	v_add_f32_dpp v43, v43, v43 quad_perm:[1,0,3,2] row_mask:0xf bank_mask:0xf bound_ctrl:1
	v_add_f32_dpp v80, v80, v80 quad_perm:[2,3,0,1] row_mask:0xf bank_mask:0xf bound_ctrl:1
	v_add_f32_dpp v15, v15, v15 row_half_mirror row_mask:0xf bank_mask:0xf bound_ctrl:1
	v_add_f32_e32 v81, v103, v81
	v_add_f32_dpp v43, v43, v43 quad_perm:[2,3,0,1] row_mask:0xf bank_mask:0xf bound_ctrl:1
	v_add_f32_dpp v80, v80, v80 row_half_mirror row_mask:0xf bank_mask:0xf bound_ctrl:1
	v_add_f32_dpp v15, v15, v15 row_mirror row_mask:0xf bank_mask:0xf bound_ctrl:1
	v_add_f32_dpp v81, v81, v81 quad_perm:[1,0,3,2] row_mask:0xf bank_mask:0xf bound_ctrl:1
	v_add_f32_dpp v43, v43, v43 row_half_mirror row_mask:0xf bank_mask:0xf bound_ctrl:1
	v_add_f32_dpp v80, v80, v80 row_mirror row_mask:0xf bank_mask:0xf bound_ctrl:1
	v_fmamk_f32 v15, v15, 0x3c000000, v39
	v_add_f32_dpp v81, v81, v81 quad_perm:[2,3,0,1] row_mask:0xf bank_mask:0xf bound_ctrl:1
	v_add_f32_dpp v43, v43, v43 row_mirror row_mask:0xf bank_mask:0xf bound_ctrl:1
	v_fmamk_f32 v80, v80, 0x3c000000, v39
	v_mul_f32_e32 v82, 0x4f800000, v15
	v_cmp_gt_f32_e64 s[8:9], s42, v15
	v_add_f32_dpp v81, v81, v81 row_half_mirror row_mask:0xf bank_mask:0xf bound_ctrl:1
	v_fmamk_f32 v43, v43, 0x3c000000, v39
	v_mul_f32_e32 v84, 0x4f800000, v80
	v_cmp_gt_f32_e64 s[4:5], s42, v80
	v_cndmask_b32_e64 v15, v15, v82, s[8:9]
	v_add_f32_dpp v81, v81, v81 row_mirror row_mask:0xf bank_mask:0xf bound_ctrl:1
	v_mul_f32_e32 v83, 0x4f800000, v43
	v_cmp_gt_f32_e32 vcc, s42, v43
	v_cndmask_b32_e64 v80, v80, v84, s[4:5]
	v_sqrt_f32_e32 v82, v15
	v_fmamk_f32 v81, v81, 0x3c000000, v39
	v_cndmask_b32_e32 v43, v43, v83, vcc
	v_sqrt_f32_e32 v84, v80
	v_mul_f32_e32 v85, 0x4f800000, v81
	v_cmp_gt_f32_e64 s[6:7], s42, v81
	v_sqrt_f32_e32 v83, v43
	v_add_u32_e32 v86, -1, v82
	v_cndmask_b32_e64 v81, v81, v85, s[6:7]
	v_sqrt_f32_e32 v85, v81
	v_add_u32_e32 v87, 1, v82
	v_add_u32_e32 v96, -1, v84
	v_fma_f32 v102, -v86, v82, v15
	v_add_u32_e32 v94, -1, v83
	v_add_u32_e32 v97, 1, v84
	v_fma_f32 v103, -v87, v82, v15
	v_fma_f32 v106, -v96, v84, v80
	v_cmp_ge_f32_e64 s[10:11], 0, v102
	v_add_u32_e32 v95, 1, v83
	v_fma_f32 v104, -v94, v83, v43
	v_fma_f32 v107, -v97, v84, v80
	v_cndmask_b32_e64 v82, v82, v86, s[10:11]
	v_cmp_ge_f32_e64 s[12:13], 0, v106
	v_cmp_lt_f32_e64 s[16:17], 0, v103
	v_add_u32_e32 v98, -1, v85
	v_fma_f32 v105, -v95, v83, v43
	v_cmp_ge_f32_e64 s[10:11], 0, v104
	v_cndmask_b32_e64 v84, v84, v96, s[12:13]
	v_cmp_lt_f32_e64 s[12:13], 0, v107
	v_cndmask_b32_e64 v82, v82, v87, s[16:17]
	v_add_u32_e32 v99, 1, v85
	v_fma_f32 v110, -v98, v85, v81
	v_cndmask_b32_e64 v83, v83, v94, s[10:11]
	v_cmp_lt_f32_e64 s[10:11], 0, v105
	v_cndmask_b32_e64 v84, v84, v97, s[12:13]
	v_mul_f32_e32 v86, 0x37800000, v82
	v_fma_f32 v111, -v99, v85, v81
	v_cmp_ge_f32_e64 s[14:15], 0, v110
	v_cndmask_b32_e64 v83, v83, v95, s[10:11]
	v_mul_f32_e32 v94, 0x37800000, v84
	v_cndmask_b32_e64 v82, v82, v86, s[8:9]
	v_cmp_class_f32_e64 s[8:9], v15, v40
	v_cndmask_b32_e64 v85, v85, v98, s[14:15]
	v_cmp_lt_f32_e64 s[14:15], 0, v111
	v_mul_f32_e32 v87, 0x37800000, v83
	v_cndmask_b32_e64 v84, v84, v94, s[4:5]
	v_cmp_class_f32_e64 s[4:5], v80, v40
	v_cndmask_b32_e64 v15, v82, v15, s[8:9]
	v_cndmask_b32_e64 v85, v85, v99, s[14:15]
	v_cndmask_b32_e32 v83, v83, v87, vcc
	v_cmp_class_f32_e32 vcc, v43, v40
	v_cndmask_b32_e64 v94, v84, v80, s[4:5]
	v_div_scale_f32 v80, s[4:5], v15, v15, 1.0
	v_mul_f32_e32 v95, 0x37800000, v85
	v_cndmask_b32_e32 v43, v83, v43, vcc
	v_rcp_f32_e32 v96, v80
	v_cndmask_b32_e64 v85, v85, v95, s[6:7]
	v_cmp_class_f32_e64 s[6:7], v81, v40
	v_div_scale_f32 v83, s[4:5], v43, v43, 1.0
	s_nop 0
	v_cndmask_b32_e64 v81, v85, v81, s[6:7]
	v_div_scale_f32 v85, s[6:7], v94, v94, 1.0
	v_rcp_f32_e32 v97, v83
	v_div_scale_f32 v87, s[8:9], v81, v81, 1.0
	v_rcp_f32_e32 v98, v85
	v_rcp_f32_e32 v99, v87
	v_fma_f32 v102, -v80, v96, 1.0
	v_div_scale_f32 v82, vcc, 1.0, v15, 1.0
	v_fmac_f32_e32 v96, v102, v96
	v_fma_f32 v103, -v83, v97, 1.0
	v_mul_f32_e32 v102, v82, v96
	v_div_scale_f32 v84, s[4:5], 1.0, v43, 1.0
	v_fma_f32 v104, -v85, v98, 1.0
	v_fmac_f32_e32 v97, v103, v97
	v_fma_f32 v106, -v80, v102, v82
	v_div_scale_f32 v86, s[6:7], 1.0, v94, 1.0
	v_fma_f32 v105, -v87, v99, 1.0
	v_fmac_f32_e32 v98, v104, v98
	v_mul_f32_e32 v103, v84, v97
	v_fmac_f32_e32 v102, v106, v96
	v_div_scale_f32 v95, s[8:9], 1.0, v81, 1.0
	v_fmac_f32_e32 v99, v105, v99
	v_mul_f32_e32 v104, v86, v98
	v_fma_f32 v107, -v83, v103, v84
	v_fma_f32 v80, -v80, v102, v82
	v_mul_f32_e32 v105, v95, v99
	v_fma_f32 v110, -v85, v104, v86
	v_fmac_f32_e32 v103, v107, v97
	v_div_fmas_f32 v80, v80, v96, v102
	v_fma_f32 v111, -v87, v105, v95
	v_fmac_f32_e32 v104, v110, v98
	v_fma_f32 v82, -v83, v103, v84
	v_div_fixup_f32 v80, v80, v15, 1.0
	s_mov_b64 vcc, s[4:5]
	v_fmac_f32_e32 v105, v111, v99
	v_fma_f32 v86, -v85, v104, v86
	v_div_fmas_f32 v15, v82, v97, v103
	v_pk_mul_f32 v[44:45], v[44:45], v[80:81] op_sel_hi:[1,0]
	s_mov_b64 vcc, s[6:7]
	v_lshlrev_b32_e32 v37, 16, v49
	v_lshlrev_b32_e32 v36, 16, v48
	v_and_b32_e32 v49, 0xffff0000, v49
	v_and_b32_e32 v48, 0xffff0000, v48
	v_fma_f32 v95, -v87, v105, v95
	v_pk_mul_f32 v[82:83], v[88:89], v[80:81] op_sel_hi:[1,0]
	v_pk_mul_f32 v[84:85], v[90:91], v[80:81] op_sel_hi:[1,0]
	v_pk_mul_f32 v[46:47], v[46:47], v[80:81] op_sel_hi:[1,0]
	v_div_fixup_f32 v80, v15, v43, 1.0
	v_div_fmas_f32 v15, v86, v98, v104
	v_pk_mul_f32 v[44:45], v[16:17], v[44:45]
	s_mov_b64 vcc, s[8:9]
	v_lshlrev_b32_e32 v101, 16, v51
	v_lshlrev_b32_e32 v100, 16, v50
	v_and_b32_e32 v51, 0xffff0000, v51
	v_and_b32_e32 v50, 0xffff0000, v50
	v_pk_mul_f32 v[82:83], v[0:1], v[82:83]
	v_pk_mul_f32 v[84:85], v[4:5], v[84:85]
	v_pk_mul_f32 v[46:47], v[2:3], v[46:47]
	v_pk_mul_f32 v[86:87], v[92:93], v[80:81] op_sel_hi:[1,0]
	v_pk_mul_f32 v[52:53], v[52:53], v[80:81] op_sel_hi:[1,0]
	v_pk_mul_f32 v[56:57], v[56:57], v[80:81] op_sel_hi:[1,0]
	v_pk_mul_f32 v[54:55], v[54:55], v[80:81] op_sel_hi:[1,0]
	v_div_fixup_f32 v80, v15, v94, 1.0
	v_div_fmas_f32 v15, v95, v99, v105
	v_pk_mul_f32 v[44:45], v[44:45], v[48:49]
	v_lshlrev_b32_e32 v109, 16, v61
	v_lshlrev_b32_e32 v108, 16, v60
	v_and_b32_e32 v61, 0xffff0000, v61
	v_and_b32_e32 v60, 0xffff0000, v60
	v_lshlrev_b32_e32 v113, 16, v63
	v_lshlrev_b32_e32 v112, 16, v62
	v_and_b32_e32 v63, 0xffff0000, v63
	v_and_b32_e32 v62, 0xffff0000, v62
	v_pk_mul_f32 v[36:37], v[82:83], v[36:37]
	v_pk_mul_f32 v[48:49], v[84:85], v[100:101]
	v_pk_mul_f32 v[46:47], v[46:47], v[50:51]
	v_pk_mul_f32 v[50:51], v[0:1], v[86:87]
	v_pk_mul_f32 v[52:53], v[16:17], v[52:53]
	v_pk_mul_f32 v[56:57], v[4:5], v[56:57]
	v_pk_mul_f32 v[54:55], v[2:3], v[54:55]
	v_pk_mul_f32 v[58:59], v[58:59], v[80:81] op_sel_hi:[1,0]
	v_pk_mul_f32 v[64:65], v[64:65], v[80:81] op_sel_hi:[1,0]
	v_pk_mul_f32 v[68:69], v[68:69], v[80:81] op_sel_hi:[1,0]
	v_pk_mul_f32 v[66:67], v[66:67], v[80:81] op_sel_hi:[1,0]
	v_div_fixup_f32 v80, v15, v81, 1.0
	v_bfe_u32 v81, v45, 16, 1
	v_lshlrev_b32_e32 v121, 16, v75
	v_lshlrev_b32_e32 v120, 16, v74
	v_bfe_u32 v15, v47, 16, 1
	v_bfe_u32 v43, v46, 16, 1
	v_bfe_u32 v83, v36, 16, 1
	v_bfe_u32 v84, v37, 16, 1
	v_bfe_u32 v85, v48, 16, 1
	v_bfe_u32 v86, v49, 16, 1
	v_pk_mul_f32 v[50:51], v[50:51], v[108:109]
	v_pk_mul_f32 v[52:53], v[52:53], v[60:61]
	v_pk_mul_f32 v[56:57], v[56:57], v[112:113]
	v_pk_mul_f32 v[54:55], v[54:55], v[62:63]
	v_pk_mul_f32 v[58:59], v[0:1], v[58:59]
	v_pk_mul_f32 v[60:61], v[16:17], v[64:65]
	v_pk_mul_f32 v[62:63], v[4:5], v[68:69]
	v_pk_mul_f32 v[64:65], v[2:3], v[66:67]
	v_pk_mul_f32 v[66:67], v[70:71], v[80:81] op_sel_hi:[1,0]
	v_pk_mul_f32 v[70:71], v[76:77], v[80:81] op_sel_hi:[1,0]
	v_lshlrev_b32_e32 v25, 16, v29
	v_lshlrev_b32_e32 v24, 16, v28
	v_and_b32_e32 v27, 0xffff0000, v29
	v_and_b32_e32 v26, 0xffff0000, v28
	v_lshlrev_b32_e32 v29, 16, v31
	v_lshlrev_b32_e32 v28, 16, v30
	v_and_b32_e32 v75, 0xffff0000, v75
	v_and_b32_e32 v74, 0xffff0000, v74
	v_bfe_u32 v82, v44, 16, 1
	v_pk_mul_f32 v[68:69], v[72:73], v[80:81] op_sel_hi:[1,0]
	v_pk_mul_f32 v[72:73], v[78:79], v[80:81] op_sel_hi:[1,0]
	v_add3_u32 v77, v45, v81, s43
	v_add3_u32 v43, v46, v43, s43
	v_add3_u32 v15, v47, v15, s43
	v_add3_u32 v78, v49, v86, s43
	v_add3_u32 v79, v48, v85, s43
	v_add3_u32 v80, v37, v84, s43
	v_add3_u32 v81, v36, v83, s43
	v_bfe_u32 v86, v50, 16, 1
	v_bfe_u32 v87, v51, 16, 1
	v_bfe_u32 v88, v56, 16, 1
	v_bfe_u32 v89, v57, 16, 1
	v_pk_mul_f32 v[32:33], v[58:59], v[32:33]
	v_pk_mul_f32 v[36:37], v[62:63], v[120:121]
	v_pk_mul_f32 v[46:47], v[0:1], v[66:67]
	v_pk_mul_f32 v[58:59], v[4:5], v[70:71]
	v_and_b32_e32 v31, 0xffff0000, v31
	v_and_b32_e32 v30, 0xffff0000, v30
	v_add3_u32 v76, v44, v82, s43
	v_bfe_u32 v82, v55, 16, 1
	v_bfe_u32 v83, v54, 16, 1
	v_bfe_u32 v84, v53, 16, 1
	v_bfe_u32 v85, v52, 16, 1
	v_pk_mul_f32 v[34:35], v[60:61], v[34:35]
	v_pk_mul_f32 v[44:45], v[64:65], v[74:75]
	v_pk_mul_f32 v[48:49], v[16:17], v[68:69]
	v_pk_mul_f32 v[60:61], v[2:3], v[72:73]
	v_lshrrev_b32_e32 v62, 16, v81
	v_lshrrev_b32_e32 v63, 16, v80
	v_lshrrev_b32_e32 v64, 16, v79
	v_lshrrev_b32_e32 v65, 16, v78
	v_add3_u32 v57, v57, v89, s43
	v_add3_u32 v56, v56, v88, s43
	v_add3_u32 v51, v51, v87, s43
	v_add3_u32 v50, v50, v86, s43
	v_bfe_u32 v70, v32, 16, 1
	v_bfe_u32 v71, v33, 16, 1
	v_bfe_u32 v72, v36, 16, 1
	v_bfe_u32 v73, v37, 16, 1
	v_pk_mul_f32 v[46:47], v[46:47], v[24:25]
	v_pk_mul_f32 v[28:29], v[58:59], v[28:29]
	v_add3_u32 v52, v52, v85, s43
	v_add3_u32 v53, v53, v84, s43
	v_add3_u32 v54, v54, v83, s43
	v_add3_u32 v55, v55, v82, s43
	v_bfe_u32 v66, v45, 16, 1
	v_bfe_u32 v67, v44, 16, 1
	v_bfe_u32 v68, v35, 16, 1
	v_bfe_u32 v69, v34, 16, 1
	v_pk_mul_f32 v[48:49], v[48:49], v[26:27]
	v_pk_mul_f32 v[30:31], v[60:61], v[30:31]
	v_and_or_b32 v27, v15, s29, v65
	v_and_or_b32 v26, v43, s29, v64
	v_and_or_b32 v25, v77, s29, v63
	v_and_or_b32 v24, v76, s29, v62
	v_lshrrev_b32_e32 v15, 16, v50
	v_lshrrev_b32_e32 v43, 16, v51
	v_lshrrev_b32_e32 v50, 16, v56
	v_lshrrev_b32_e32 v51, 16, v57
	v_add3_u32 v37, v37, v73, s43
	v_add3_u32 v36, v36, v72, s43
	v_add3_u32 v33, v33, v71, s43
	v_add3_u32 v32, v32, v70, s43
	v_bfe_u32 v60, v46, 16, 1
	v_bfe_u32 v61, v47, 16, 1
	v_bfe_u32 v62, v28, 16, 1
	v_bfe_u32 v63, v29, 16, 1
	global_store_dwordx4 v[22:23], v[24:27], off sc1
	s_nop 1
	v_add3_u32 v34, v34, v69, s43
	v_add3_u32 v35, v35, v68, s43
	v_add3_u32 v44, v44, v67, s43
	v_add3_u32 v45, v45, v66, s43
	v_bfe_u32 v56, v31, 16, 1
	v_bfe_u32 v57, v30, 16, 1
	v_bfe_u32 v58, v49, 16, 1
	v_bfe_u32 v59, v48, 16, 1
	v_and_or_b32 v25, v55, s29, v51
	v_and_or_b32 v24, v54, s29, v50
	v_and_or_b32 v23, v53, s29, v43
	v_and_or_b32 v22, v52, s29, v15
	v_lshrrev_b32_e32 v15, 16, v32
	v_lshrrev_b32_e32 v26, 16, v33
	v_lshrrev_b32_e32 v27, 16, v36
	v_lshrrev_b32_e32 v32, 16, v37
	v_add3_u32 v29, v29, v63, s43
	v_add3_u32 v28, v28, v62, s43
	v_add3_u32 v37, v47, v61, s43
	v_add3_u32 v43, v46, v60, s43
	global_store_dwordx4 v[20:21], v[22:25], off sc1
	s_nop 1
	v_add3_u32 v33, v48, v59, s43
	v_add3_u32 v36, v49, v58, s43
	v_add3_u32 v30, v30, v57, s43
	v_add3_u32 v31, v31, v56, s43
	v_and_or_b32 v23, v45, s29, v32
	v_and_or_b32 v22, v44, s29, v27
	v_and_or_b32 v21, v35, s29, v26
	v_and_or_b32 v20, v34, s29, v15
	v_lshrrev_b32_e32 v15, 16, v43
	v_lshrrev_b32_e32 v24, 16, v37
	v_lshrrev_b32_e32 v25, 16, v28
	v_lshrrev_b32_e32 v26, 16, v29
	global_store_dwordx4 v[18:19], v[20:23], off sc1
	s_nop 1
	v_and_or_b32 v21, v31, s29, v26
	v_and_or_b32 v20, v30, s29, v25
	v_and_or_b32 v19, v36, s29, v24
	v_and_or_b32 v18, v33, s29, v15
	global_store_dwordx4 v[6:7], v[18:21], off sc1
	s_nop 1
	s_cbranch_scc1 .LBB0_617
